# norm rows loop: x loads of rows 1 and 2 issued with the iteration's first load group (fresh registers, copies at the old sites) - one serial round trip fewer per row block
# speedup vs baseline: 1.0019x; 1.0001x over previous
.LBB0_180:
	v_readlane_b32 s0, v253, 39
	s_movk_i32 s3, 0x4000
	v_add_u32_e32 v0, 0xffffc000, v50
	v_mov_b32_e32 v34, s0
	v_readlane_b32 s0, v253, 37
	v_cmp_gt_i32_e32 vcc, s3, v50
	v_min_i32_e32 v12, 0x4000, v50
	v_mov_b32_e32 v35, s0
	v_readlane_b32 s0, v253, 40
	v_cndmask_b32_e32 v3, 0, v51, vcc
	v_cndmask_b32_e32 v2, v0, v50, vcc
	v_mov_b32_e32 v36, s0
	v_readlane_b32 s0, v253, 38
	v_cndmask_b32_e32 v5, v34, v35, vcc
	v_lshlrev_b64 v[2:3], 12, v[2:3]
	v_mov_b32_e32 v37, s0
	v_cndmask_b32_e32 v4, v36, v37, vcc
	v_lshl_add_u64 v[2:3], v[4:5], 0, v[2:3]
	v_lshlrev_b32_e32 v0, 2, v52
	v_lshl_add_u64 v[2:3], v[2:3], 0, v[0:1]
	global_load_dwordx4 v[30:33], v[2:3], off
	global_load_dwordx4 v[26:29], v[2:3], off offset:1024
	s_waitcnt lgkmcnt(0)
	global_load_dwordx4 v[18:21], v[2:3], off offset:2048
	s_nop 0
	global_load_dwordx4 v[2:5], v[2:3], off offset:3072
	s_nop 0
	global_load_dwordx4 v[80:83], v[54:55], off
	v_lshl_add_u64 v[10:11], s[42:43], 0, v[50:51]
	v_ashrrev_i32_e32 v12, 11, v12
	v_readlane_b32 s0, v253, 41
	v_mov_b64_e32 v[6:7], s[36:37]
	v_lshl_add_u64 v[70:71], s[42:43], 0, v[10:11]
	v_add_u32_e32 v11, s0, v12
	s_movk_i32 s0, 0x3000
	v_mad_i64_i32 v[6:7], s[0:1], v11, s0, v[6:7]
	s_mov_b64 s[0:1], 0x1000
	s_nop 0
	v_lshl_add_u64 v[92:93], v[6:7], 0, s[0:1]
	v_lshl_add_u64 v[12:13], v[92:93], 0, v[0:1]
	global_load_dwordx4 v[84:87], v[12:13], off
	v_lshl_add_u64 v[94:95], v[6:7], 0, v[0:1]
	global_load_dwordx4 v[88:91], v[94:95], off
	v_mov_b32_e32 v65, v1
	v_mov_b32_e32 v67, v1
	v_mov_b32_e32 v69, v1
	global_load_dwordx4 v[98:101], v[54:55], off offset:1024
	v_lshl_add_u64 v[102:103], v[92:93], 0, v[64:65]
	global_load_dwordx4 v[102:105], v[102:103], off
	global_load_dwordx4 v[106:109], v[94:95], off offset:1024
	global_load_dwordx4 v[110:113], v[54:55], off offset:2048
	v_lshl_add_u64 v[114:115], v[92:93], 0, v[66:67]
	global_load_dwordx4 v[114:117], v[114:115], off
	global_load_dwordx4 v[118:121], v[94:95], off offset:2048
	global_load_dwordx4 v[122:125], v[54:55], off offset:3072
	v_lshl_add_u64 v[126:127], v[92:93], 0, v[68:69]
	global_load_dwordx4 v[126:129], v[126:127], off
	global_load_dwordx4 v[130:133], v[94:95], off offset:3072
	s_movk_i32 s2, 0x4800
	v_cmp_gt_i32_e64 s[4:5], s2, v10
	v_cmp_gt_i32_e32 vcc, s2, v70
	s_nop 1
	v_cndmask_b32_e64 v168, v50, v10, s[4:5]
	v_cndmask_b32_e32 v169, v50, v70, vcc
	v_cmp_gt_i32_e64 s[4:5], s3, v168
	v_cmp_gt_i32_e32 vcc, s3, v169
	v_ashrrev_i32_e32 v171, 31, v168
	v_add_u32_e32 v170, 0xffffc000, v168
	v_ashrrev_i32_e32 v175, 31, v169
	v_add_u32_e32 v174, 0xffffc000, v169
	v_cndmask_b32_e64 v171, 0, v171, s[4:5]
	v_cndmask_b32_e64 v170, v170, v168, s[4:5]
	v_cndmask_b32_e64 v173, v34, v35, s[4:5]
	v_cndmask_b32_e64 v172, v36, v37, s[4:5]
	v_cndmask_b32_e32 v175, 0, v175, vcc
	v_cndmask_b32_e32 v174, v174, v169, vcc
	v_cndmask_b32_e32 v177, v34, v35, vcc
	v_cndmask_b32_e32 v176, v36, v37, vcc
	v_lshlrev_b64 v[170:171], 12, v[170:171]
	v_lshlrev_b64 v[174:175], 12, v[174:175]
	v_lshl_add_u64 v[170:171], v[172:173], 0, v[170:171]
	v_lshl_add_u64 v[174:175], v[176:177], 0, v[174:175]
	v_lshl_add_u64 v[170:171], v[170:171], 0, v[0:1]
	v_lshl_add_u64 v[174:175], v[174:175], 0, v[0:1]
	global_load_dwordx4 v[134:137], v[170:171], off
	global_load_dwordx4 v[138:141], v[170:171], off offset:1024
	global_load_dwordx4 v[142:145], v[170:171], off offset:2048
	global_load_dwordx4 v[146:149], v[170:171], off offset:3072
	global_load_dwordx4 v[150:153], v[174:175], off
	global_load_dwordx4 v[154:157], v[174:175], off offset:1024
	global_load_dwordx4 v[158:161], v[174:175], off offset:2048
	global_load_dwordx4 v[164:167], v[174:175], off offset:3072
	v_lshl_add_u64 v[8:9], v[62:63], 0, v[58:59]
	s_mov_b32 s0, 0x133c000
	v_add_co_u32_e32 v72, vcc, s0, v8
	s_movk_i32 s2, 0x4800
	s_nop 0
	v_addc_co_u32_e32 v73, vcc, 0, v9, vcc
	v_cmp_gt_i32_e64 s[0:1], s2, v10
	v_cmp_gt_i32_e32 vcc, s2, v70
	v_mov_b32_e32 v65, v1
	v_cndmask_b32_e64 v38, v50, v10, s[0:1]
	v_ashrrev_i32_e32 v39, 31, v38
	v_add_u32_e32 v40, 0xffffc000, v38
	v_cmp_gt_i32_e64 s[4:5], s3, v38
	s_waitcnt vmcnt(14)
	v_mov_b32_e32 v8, v31
	s_waitcnt vmcnt(13)
	v_mov_b32_e32 v9, v27
	v_mov_b32_e32 v6, v30
	v_mov_b32_e32 v7, v26
	s_waitcnt vmcnt(12)
	v_mov_b32_e32 v14, v19
	s_waitcnt vmcnt(11)
	v_mov_b32_e32 v15, v3
	v_pk_mul_f32 v[8:9], v[8:9], v[8:9]
	v_mov_b32_e32 v10, v32
	v_mov_b32_e32 v11, v28
	v_mov_b32_e32 v12, v18
	v_mov_b32_e32 v13, v2
	v_pk_mul_f32 v[14:15], v[14:15], v[14:15]
	v_pk_fma_f32 v[6:7], v[6:7], v[6:7], v[8:9]
	v_mov_b32_e32 v16, v33
	v_mov_b32_e32 v17, v29
	v_mov_b32_e32 v22, v20
	v_mov_b32_e32 v23, v4
	v_pk_fma_f32 v[8:9], v[12:13], v[12:13], v[14:15]
	v_pk_fma_f32 v[6:7], v[10:11], v[10:11], v[6:7]
	v_mov_b32_e32 v24, v21
	v_mov_b32_e32 v25, v5
	v_pk_fma_f32 v[8:9], v[22:23], v[22:23], v[8:9]
	v_pk_fma_f32 v[6:7], v[16:17], v[16:17], v[6:7]
	v_pk_fma_f32 v[8:9], v[24:25], v[24:25], v[8:9]
	v_add_f32_e32 v6, v6, v7
	v_add_f32_e32 v6, v6, v8
	v_add_f32_e32 v8, v6, v9
	v_mov_b32_e32 v9, v8
	s_nop 1
	v_permlane32_swap_b32_e32 v8, v9
	v_cndmask_b32_e32 v10, v50, v70, vcc
	v_cndmask_b32_e64 v7, 0, v39, s[4:5]
	v_cndmask_b32_e64 v6, v40, v38, s[4:5]
	v_add_u32_e32 v14, 0xffffc000, v10
	s_waitcnt lgkmcnt(0)
	v_add_f32_e32 v11, v8, v9
	v_mov_b32_e32 v12, v11
	s_nop 1
	v_permlane16_swap_b32_e32 v11, v12
	v_cndmask_b32_e64 v9, v34, v35, s[4:5]
	v_cndmask_b32_e64 v8, v36, v37, s[4:5]
	v_cmp_gt_i32_e64 s[4:5], s3, v10
	v_ashrrev_i32_e32 v13, 31, v10
	s_waitcnt lgkmcnt(0)
	v_add_f32_e32 v15, v11, v12
	s_nop 1
	v_mov_b32_dpp v16, v15 row_ror:8 row_mask:0xf bank_mask:0xf
	v_cndmask_b32_e64 v10, v14, v10, s[4:5]
	v_cndmask_b32_e64 v11, 0, v13, s[4:5]
	v_lshlrev_b64 v[6:7], 12, v[6:7]
	v_lshl_add_u64 v[6:7], v[8:9], 0, v[6:7]
	s_waitcnt lgkmcnt(0)
	v_add_f32_e32 v14, v15, v16
	s_nop 1
	v_mov_b32_dpp v15, v14 row_ror:4 row_mask:0xf bank_mask:0xf
	v_lshlrev_b64 v[8:9], 12, v[10:11]
	v_cndmask_b32_e64 v13, v34, v35, s[4:5]
	v_cndmask_b32_e64 v12, v36, v37, s[4:5]
	v_lshl_add_u64 v[8:9], v[12:13], 0, v[8:9]
	s_waitcnt lgkmcnt(0)
	v_add_f32_e32 v10, v14, v15
	s_nop 1
	v_mov_b32_dpp v11, v10 quad_perm:[2,3,0,1] row_mask:0xf bank_mask:0xf
	v_lshl_add_u64 v[6:7], v[6:7], 0, v[0:1]
	v_lshl_add_u64 v[8:9], v[8:9], 0, v[0:1]
	s_waitcnt vmcnt(0)
	v_mov_b64_e32 v[46:47], v[134:135]
	v_mov_b64_e32 v[48:49], v[136:137]
	v_mov_b64_e32 v[42:43], v[138:139]
	v_mov_b64_e32 v[44:45], v[140:141]
	v_mov_b64_e32 v[38:39], v[142:143]
	v_mov_b64_e32 v[40:41], v[144:145]
	v_mov_b64_e32 v[34:35], v[146:147]
	v_mov_b64_e32 v[36:37], v[148:149]
	v_mov_b64_e32 v[22:23], v[150:151]
	v_mov_b64_e32 v[24:25], v[152:153]
	v_mov_b64_e32 v[14:15], v[154:155]
	v_mov_b64_e32 v[16:17], v[156:157]
	s_waitcnt lgkmcnt(0)
	v_add_f32_e32 v10, v10, v11
	s_nop 1
	v_mov_b32_dpp v11, v10 quad_perm:[1,0,3,2] row_mask:0xf bank_mask:0xf
	s_waitcnt vmcnt(7)
	v_pk_add_f32 v[84:85], v[84:85], 1.0 op_sel_hi:[1,0]
	v_pk_add_f32 v[86:87], v[86:87], 1.0 op_sel_hi:[1,0]
	s_waitcnt lgkmcnt(0)
	v_add_f32_e32 v6, v10, v11
	v_fmamk_f32 v6, v6, 0x3a800000, v196
	v_mul_f32_e32 v7, 0x4b800000, v6
	v_cmp_gt_f32_e64 s[4:5], s33, v6
	s_waitcnt vmcnt(1)
	v_mul_f32_e32 v71, v23, v23
	v_cndmask_b32_e64 v6, v6, v7, s[4:5]
	v_rsq_f32_e32 v67, v6
	v_mov_b64_e32 v[10:11], v[158:159]
	v_mov_b64_e32 v[12:13], v[160:161]
	v_mov_b64_e32 v[6:7], v[164:165]
	v_mov_b64_e32 v[8:9], v[166:167]
	s_waitcnt vmcnt(2)
	v_mul_f32_e32 v79, v15, v15
	v_fmac_f32_e32 v71, v22, v22
	v_mul_f32_e32 v69, 0x45800000, v67
	v_cndmask_b32_e64 v96, v67, v69, s[4:5]
	v_pk_mul_f32 v[30:31], v[30:31], v[96:97] op_sel_hi:[1,0]
	v_pk_mul_f32 v[32:33], v[32:33], v[96:97] op_sel_hi:[1,0]
	v_pk_mul_f32 v[30:31], v[30:31], v[80:81]
	v_pk_mul_f32 v[32:33], v[32:33], v[82:83]
	v_pk_fma_f32 v[30:31], v[30:31], v[84:85], v[88:89]
	v_pk_fma_f32 v[32:33], v[32:33], v[86:87], v[90:91]
	v_cvt_pk_bf16_f32 v30, v30, v31
	v_cvt_pk_bf16_f32 v31, v32, v33
	global_store_dwordx2 v[72:73], v[30:31], off
	s_nop 0
	v_pk_mul_f32 v[26:27], v[26:27], v[96:97] op_sel_hi:[1,0]
	v_pk_mul_f32 v[28:29], v[28:29], v[96:97] op_sel_hi:[1,0]
	v_mov_b32_e32 v67, v1
	v_pk_mul_f32 v[18:19], v[18:19], v[96:97] op_sel_hi:[1,0]
	v_pk_mul_f32 v[20:21], v[20:21], v[96:97] op_sel_hi:[1,0]
	v_mov_b32_e32 v69, v1
	v_fmac_f32_e32 v79, v14, v14
	v_fmac_f32_e32 v71, v24, v24
	v_fmac_f32_e32 v79, v16, v16
	v_fmac_f32_e32 v71, v25, v25
	v_fmac_f32_e32 v79, v17, v17
	v_pk_mul_f32 v[2:3], v[2:3], v[96:97] op_sel_hi:[1,0]
	v_pk_mul_f32 v[4:5], v[4:5], v[96:97] op_sel_hi:[1,0]
	s_waitcnt vmcnt(2)
	v_pk_mul_f32 v[26:27], v[26:27], v[98:99]
	v_pk_mul_f32 v[28:29], v[28:29], v[100:101]
	s_waitcnt vmcnt(1)
	v_pk_add_f32 v[30:31], v[102:103], 1.0 op_sel_hi:[1,0]
	v_pk_add_f32 v[32:33], v[104:105], 1.0 op_sel_hi:[1,0]
	s_waitcnt vmcnt(0)
	v_pk_fma_f32 v[26:27], v[26:27], v[30:31], v[106:107]
	v_pk_fma_f32 v[28:29], v[28:29], v[32:33], v[108:109]
	v_cvt_pk_bf16_f32 v26, v26, v27
	v_cvt_pk_bf16_f32 v27, v28, v29
	global_store_dwordx2 v[72:73], v[26:27], off offset:512
	s_nop 0
	s_waitcnt vmcnt(2)
	v_pk_mul_f32 v[18:19], v[18:19], v[110:111]
	v_pk_mul_f32 v[20:21], v[20:21], v[112:113]
	s_waitcnt vmcnt(1)
	v_pk_add_f32 v[26:27], v[114:115], 1.0 op_sel_hi:[1,0]
	v_pk_add_f32 v[28:29], v[116:117], 1.0 op_sel_hi:[1,0]
	s_waitcnt vmcnt(0)
	v_pk_fma_f32 v[18:19], v[18:19], v[26:27], v[118:119]
	v_pk_fma_f32 v[20:21], v[20:21], v[28:29], v[120:121]
	v_cvt_pk_bf16_f32 v18, v18, v19
	v_cvt_pk_bf16_f32 v19, v20, v21
	global_store_dwordx2 v[72:73], v[18:19], off offset:1024
	v_mul_f32_e32 v18, v47, v47
	v_mul_f32_e32 v19, v43, v43
	v_mul_f32_e32 v20, v39, v39
	v_fmac_f32_e32 v18, v46, v46
	v_fmac_f32_e32 v19, v42, v42
	v_mul_f32_e32 v84, v11, v11
	v_mul_f32_e32 v21, v35, v35
	v_fmac_f32_e32 v20, v38, v38
	v_mul_f32_e32 v85, v7, v7
	v_fmac_f32_e32 v18, v48, v48
	v_fmac_f32_e32 v19, v44, v44
	v_fmac_f32_e32 v84, v10, v10
	v_fmac_f32_e32 v21, v34, v34
	v_fmac_f32_e32 v20, v40, v40
	v_fmac_f32_e32 v85, v6, v6
	v_fmac_f32_e32 v18, v49, v49
	v_fmac_f32_e32 v19, v45, v45
	v_fmac_f32_e32 v84, v12, v12
	v_fmac_f32_e32 v21, v36, v36
	v_fmac_f32_e32 v20, v41, v41
	v_fmac_f32_e32 v85, v8, v8
	v_add_f32_e32 v18, v18, v19
	v_fmac_f32_e32 v84, v13, v13
	v_add_f32_e32 v19, v71, v79
	v_fmac_f32_e32 v21, v37, v37
	v_fmac_f32_e32 v85, v9, v9
	v_add_f32_e32 v18, v18, v20
	v_add_f32_e32 v19, v19, v84
	v_add_f32_e32 v18, v18, v21
	v_add_f32_e32 v19, v19, v85
	v_mov_b32_e32 v20, v18
	s_nop 1
	v_permlane32_swap_b32_e32 v18, v20
	v_mov_b32_e32 v21, v19
	s_nop 1
	v_permlane32_swap_b32_e32 v19, v21
	s_waitcnt lgkmcnt(1)
	v_add_f32_e32 v18, v18, v20
	s_waitcnt lgkmcnt(0)
	v_add_f32_e32 v19, v19, v21
	v_mov_b32_e32 v20, v18
	s_nop 1
	v_permlane16_swap_b32_e32 v18, v20
	v_mov_b32_e32 v21, v19
	s_nop 1
	v_permlane16_swap_b32_e32 v19, v21
	s_waitcnt lgkmcnt(1)
	v_add_f32_e32 v18, v18, v20
	s_waitcnt lgkmcnt(0)
	v_add_f32_e32 v19, v19, v21
	v_mov_b32_dpp v20, v18 row_ror:8 row_mask:0xf bank_mask:0xf
	s_nop 0
	v_mov_b32_dpp v21, v19 row_ror:8 row_mask:0xf bank_mask:0xf
	s_waitcnt lgkmcnt(1)
	v_add_f32_e32 v18, v18, v20
	s_waitcnt lgkmcnt(0)
	v_add_f32_e32 v19, v19, v21
	v_mov_b32_dpp v20, v18 row_ror:4 row_mask:0xf bank_mask:0xf
	s_nop 0
	v_mov_b32_dpp v21, v19 row_ror:4 row_mask:0xf bank_mask:0xf
	s_waitcnt lgkmcnt(1)
	v_add_f32_e32 v18, v18, v20
	s_waitcnt lgkmcnt(0)
	v_add_f32_e32 v19, v19, v21
	v_mov_b32_dpp v20, v18 quad_perm:[2,3,0,1] row_mask:0xf bank_mask:0xf
	s_nop 0
	v_mov_b32_dpp v21, v19 quad_perm:[2,3,0,1] row_mask:0xf bank_mask:0xf
	s_waitcnt lgkmcnt(1)
	v_add_f32_e32 v20, v18, v20
	s_waitcnt lgkmcnt(0)
	v_add_f32_e32 v18, v19, v21
	v_mov_b32_dpp v21, v20 quad_perm:[1,0,3,2] row_mask:0xf bank_mask:0xf
	s_nop 0
	v_mov_b32_dpp v19, v18 quad_perm:[1,0,3,2] row_mask:0xf bank_mask:0xf
	s_waitcnt vmcnt(2)
	v_pk_mul_f32 v[2:3], v[2:3], v[122:123]
	v_pk_mul_f32 v[4:5], v[4:5], v[124:125]
	s_waitcnt vmcnt(1)
	v_pk_add_f32 v[26:27], v[126:127], 1.0 op_sel_hi:[1,0]
	v_pk_add_f32 v[28:29], v[128:129], 1.0 op_sel_hi:[1,0]
	s_waitcnt vmcnt(0)
	v_pk_fma_f32 v[2:3], v[2:3], v[26:27], v[130:131]
	v_pk_fma_f32 v[4:5], v[4:5], v[28:29], v[132:133]
	v_cvt_pk_bf16_f32 v2, v2, v3
	v_cvt_pk_bf16_f32 v3, v4, v5
	global_store_dwordx2 v[72:73], v[2:3], off offset:1536
	s_and_saveexec_b64 s[12:13], s[0:1]
	s_cbranch_execz .LBB0_182
	v_add_u32_e32 v2, s42, v50
	v_min_i32_e32 v2, 0x4000, v2
	v_ashrrev_i32_e32 v2, 11, v2
	v_readlane_b32 s0, v253, 41
	s_waitcnt lgkmcnt(1)
	v_add_f32_e32 v71, v20, v21
	v_fmamk_f32 v71, v71, 0x3a800000, v196
	v_add_u32_e32 v4, s0, v2
	v_mov_b64_e32 v[2:3], s[36:37]
	s_movk_i32 s0, 0x3000
	v_mad_i64_i32 v[30:31], s[0:1], v4, s0, v[2:3]
	s_mov_b64 s[0:1], 0x1000
	s_nop 0
	v_lshl_add_u64 v[72:73], v[30:31], 0, s[0:1]
	v_lshl_add_u64 v[26:27], v[72:73], 0, v[0:1]
	global_load_dwordx4 v[2:5], v[54:55], off
	v_lshl_add_u64 v[80:81], v[30:31], 0, v[0:1]
	global_load_dwordx4 v[26:29], v[26:27], off
	v_mul_f32_e32 v79, 0x4b800000, v71
	global_load_dwordx4 v[30:33], v[80:81], off
	v_mov_b32_e32 v65, v1
	v_mov_b32_e32 v67, v1
	v_mov_b32_e32 v69, v1
	global_load_dwordx4 v[98:101], v[54:55], off offset:1024
	v_lshl_add_u64 v[102:103], v[72:73], 0, v[64:65]
	global_load_dwordx4 v[102:105], v[102:103], off
	global_load_dwordx4 v[106:109], v[80:81], off offset:1024
	global_load_dwordx4 v[110:113], v[54:55], off offset:2048
	v_lshl_add_u64 v[114:115], v[72:73], 0, v[66:67]
	global_load_dwordx4 v[114:117], v[114:115], off
	global_load_dwordx4 v[118:121], v[80:81], off offset:2048
	global_load_dwordx4 v[122:125], v[54:55], off offset:3072
	v_lshl_add_u64 v[126:127], v[72:73], 0, v[68:69]
	global_load_dwordx4 v[126:129], v[126:127], off
	global_load_dwordx4 v[130:133], v[80:81], off offset:3072
	v_cmp_gt_f32_e64 s[0:1], s33, v71
	v_lshl_add_u64 v[20:21], v[60:61], 0, v[58:59]
	v_cndmask_b32_e64 v71, v71, v79, s[0:1]
	v_rsq_f32_e32 v71, v71
	s_mov_b32 s2, 0x133c000
	v_add_co_u32_e64 v20, s[4:5], s2, v20
	v_mul_f32_e32 v65, 0x45800000, v71
	v_cndmask_b32_e64 v84, v71, v65, s[0:1]
	v_pk_mul_f32 v[46:47], v[46:47], v[84:85] op_sel_hi:[1,0]
	v_pk_mul_f32 v[48:49], v[48:49], v[84:85] op_sel_hi:[1,0]
	v_addc_co_u32_e64 v21, s[4:5], 0, v21, s[4:5]
	v_pk_mul_f32 v[42:43], v[42:43], v[84:85] op_sel_hi:[1,0]
	v_pk_mul_f32 v[44:45], v[44:45], v[84:85] op_sel_hi:[1,0]
	v_pk_mul_f32 v[38:39], v[38:39], v[84:85] op_sel_hi:[1,0]
	v_pk_mul_f32 v[40:41], v[40:41], v[84:85] op_sel_hi:[1,0]
	v_pk_mul_f32 v[34:35], v[34:35], v[84:85] op_sel_hi:[1,0]
	v_pk_mul_f32 v[36:37], v[36:37], v[84:85] op_sel_hi:[1,0]
	s_waitcnt vmcnt(2)
	v_pk_mul_f32 v[2:3], v[46:47], v[2:3]
	v_pk_mul_f32 v[4:5], v[48:49], v[4:5]
	s_waitcnt vmcnt(1)
	v_pk_add_f32 v[26:27], v[26:27], 1.0 op_sel_hi:[1,0]
	v_pk_add_f32 v[28:29], v[28:29], 1.0 op_sel_hi:[1,0]
	s_waitcnt vmcnt(0)
	v_pk_fma_f32 v[2:3], v[2:3], v[26:27], v[30:31]
	v_pk_fma_f32 v[4:5], v[4:5], v[28:29], v[32:33]
	v_cvt_pk_bf16_f32 v2, v2, v3
	v_cvt_pk_bf16_f32 v3, v4, v5
	global_store_dwordx2 v[20:21], v[2:3], off
	s_nop 0
	s_waitcnt vmcnt(2)
	v_pk_mul_f32 v[2:3], v[42:43], v[98:99]
	s_waitcnt vmcnt(1)
	v_pk_add_f32 v[26:27], v[102:103], 1.0 op_sel_hi:[1,0]
	v_pk_mul_f32 v[4:5], v[44:45], v[100:101]
	v_pk_add_f32 v[28:29], v[104:105], 1.0 op_sel_hi:[1,0]
	s_waitcnt vmcnt(0)
	v_pk_fma_f32 v[2:3], v[2:3], v[26:27], v[106:107]
	v_pk_fma_f32 v[4:5], v[4:5], v[28:29], v[108:109]
	v_cvt_pk_bf16_f32 v2, v2, v3
	v_cvt_pk_bf16_f32 v3, v4, v5
	global_store_dwordx2 v[20:21], v[2:3], off offset:512
	s_nop 0
	s_waitcnt vmcnt(2)
	v_pk_mul_f32 v[2:3], v[38:39], v[110:111]
	s_waitcnt vmcnt(1)
	v_pk_add_f32 v[26:27], v[114:115], 1.0 op_sel_hi:[1,0]
	v_pk_mul_f32 v[4:5], v[40:41], v[112:113]
	v_pk_add_f32 v[28:29], v[116:117], 1.0 op_sel_hi:[1,0]
	s_waitcnt vmcnt(0)
	v_pk_fma_f32 v[2:3], v[2:3], v[26:27], v[118:119]
	v_pk_fma_f32 v[4:5], v[4:5], v[28:29], v[120:121]
	v_cvt_pk_bf16_f32 v2, v2, v3
	v_cvt_pk_bf16_f32 v3, v4, v5
	global_store_dwordx2 v[20:21], v[2:3], off offset:1024
	s_nop 0
	s_waitcnt vmcnt(2)
	v_pk_mul_f32 v[2:3], v[34:35], v[122:123]
	s_waitcnt vmcnt(1)
	v_pk_add_f32 v[26:27], v[126:127], 1.0 op_sel_hi:[1,0]
	v_pk_mul_f32 v[4:5], v[36:37], v[124:125]
	v_pk_add_f32 v[28:29], v[128:129], 1.0 op_sel_hi:[1,0]
	s_waitcnt vmcnt(0)
	v_pk_fma_f32 v[2:3], v[2:3], v[26:27], v[130:131]
	v_pk_fma_f32 v[4:5], v[4:5], v[28:29], v[132:133]
	v_cvt_pk_bf16_f32 v2, v2, v3
	v_cvt_pk_bf16_f32 v3, v4, v5
	global_store_dwordx2 v[20:21], v[2:3], off offset:1536
